# MLA: masked tail loop with per-wave variants (full / PV-only / idle) for the six tiles around the causal diagonal
# baseline (speedup 1.0000x reference)
.Lmf_tail:
	s_mov_b32 s18, s83
	s_mov_b32 s17, 3
	v_lshlrev_b32_e32 v241, 2, v219
	v_sub_u32_e32 v240, v198, v241
	s_add_i32 s19, s73, 31
.Lmf_mloop:
	s_add_i32 s84, s18, 0
	s_lshl_b32 s84, s84, 6
	s_cmp_gt_i32 s84, s19
	s_cbranch_scc1 .Lmf_idle_m0
	s_addk_i32 s84, 0x40
	s_cmp_gt_i32 s84, s19
	s_cbranch_scc1 .Lmf_conly_m0
	v_subrev_u32_e32 v241, s84, v240
	ds_read_b128 v[162:165], v216 offset:13312
	ds_read_b128 v[166:169], v216 offset:19968
	ds_read_b128 v[172:175], v216 offset:13344
	ds_read_b128 v[176:179], v216 offset:20000
	ds_read_b128 v[180:183], v216 offset:13376
	global_load_dwordx4 v[130:133], v235, s[14:15]
	global_load_dwordx4 v[134:137], v236, s[14:15]
	s_add_u32 s14, s14, 0x18000
	s_addc_u32 s15, s15, 0
	global_load_dwordx4 v[142:145], v237, s[12:13]
	s_add_u32 s12, s12, 0x80
	s_addc_u32 s13, s13, 0
	s_waitcnt lgkmcnt(4)
	v_mfma_f32_32x32x16_bf16 v[34:49], v[162:165], v[98:101], v[146:161]
	ds_read_b128 v[184:187], v216 offset:20032
	v_exp_f32_e32 v66, v66
	v_exp_f32_e32 v67, v67
	v_exp_f32_e32 v68, v68
	v_exp_f32_e32 v69, v69
	v_add_f32_e32 v171, v66, v171
	v_exp_f32_e32 v70, v70
	s_waitcnt lgkmcnt(4)
	v_mfma_f32_32x32x16_bf16 v[50:65], v[166:169], v[98:101], v[146:161]
	ds_read_b128 v[188:191], v216 offset:13408
	v_exp_f32_e32 v71, v71
	v_add_f32_e32 v171, v68, v171
	v_exp_f32_e32 v72, v72
	v_add_f32_e32 v197, v67, v69
	v_exp_f32_e32 v73, v73
	v_add_f32_e32 v171, v70, v171
	s_waitcnt lgkmcnt(4)
	v_mfma_f32_32x32x16_bf16 v[34:49], v[172:175], v[102:105], v[34:49]
	ds_read_b128 v[192:195], v216 offset:20064
	v_add_f32_e32 v197, v71, v197
	v_cvt_pk_bf16_f32 v66, v66, v67
	v_add_f32_e32 v171, v72, v171
	v_cvt_pk_bf16_f32 v67, v68, v69
	v_add_f32_e32 v197, v73, v197
	v_cvt_pk_bf16_f32 v68, v70, v71
	v_cvt_pk_bf16_f32 v69, v72, v73
	v_exp_f32_e32 v74, v74
	v_exp_f32_e32 v75, v75
	s_waitcnt lgkmcnt(4)
	v_mfma_f32_32x32x16_bf16 v[50:65], v[176:179], v[102:105], v[50:65]
	ds_read_b128 v[162:165], v216 offset:13440
	v_exp_f32_e32 v76, v76
	v_exp_f32_e32 v77, v77
	v_add_f32_e32 v171, v74, v171
	v_exp_f32_e32 v78, v78
	v_add_f32_e32 v197, v75, v197
	v_exp_f32_e32 v79, v79
	s_waitcnt lgkmcnt(4)
	v_mfma_f32_32x32x16_bf16 v[34:49], v[180:183], v[106:109], v[34:49]
	ds_read_b128 v[166:169], v216 offset:20096
	v_add_f32_e32 v171, v76, v171
	v_exp_f32_e32 v80, v80
	v_add_f32_e32 v197, v77, v197
	v_exp_f32_e32 v81, v81
	v_add_f32_e32 v171, v78, v171
	v_add_f32_e32 v197, v79, v197
	s_waitcnt lgkmcnt(4)
	v_mfma_f32_32x32x16_bf16 v[50:65], v[184:187], v[106:109], v[50:65]
	ds_read_b128 v[172:175], v216 offset:13472
	v_cvt_pk_bf16_f32 v74, v74, v75
	v_add_f32_e32 v171, v80, v171
	v_cvt_pk_bf16_f32 v75, v76, v77
	v_add_f32_e32 v197, v81, v197
	v_cvt_pk_bf16_f32 v76, v78, v79
	v_cvt_pk_bf16_f32 v77, v80, v81
	v_exp_f32_e32 v82, v82
	v_exp_f32_e32 v83, v83
	s_waitcnt lgkmcnt(4)
	v_mfma_f32_32x32x16_bf16 v[34:49], v[188:191], v[110:113], v[34:49]
	ds_read_b128 v[176:179], v216 offset:20128
	v_exp_f32_e32 v84, v84
	v_exp_f32_e32 v85, v85
	v_add_f32_e32 v171, v82, v171
	v_exp_f32_e32 v86, v86
	v_add_f32_e32 v197, v83, v197
	v_exp_f32_e32 v87, v87
	s_waitcnt lgkmcnt(4)
	v_mfma_f32_32x32x16_bf16 v[50:65], v[192:195], v[110:113], v[50:65]
	ds_read_b128 v[180:183], v217 offset:26624
	v_add_f32_e32 v171, v84, v171
	v_exp_f32_e32 v88, v88
	v_add_f32_e32 v197, v85, v197
	v_exp_f32_e32 v89, v89
	v_add_f32_e32 v171, v86, v171
	v_add_f32_e32 v197, v87, v197
	v_cvt_pk_bf16_f32 v82, v82, v83
	v_add_f32_e32 v171, v88, v171
	s_waitcnt lgkmcnt(4)
	v_mfma_f32_32x32x16_bf16 v[34:49], v[162:165], v[114:117], v[34:49]
	ds_read_b128 v[184:187], v217 offset:31232
	v_cvt_pk_bf16_f32 v83, v84, v85
	v_add_f32_e32 v197, v89, v197
	v_cvt_pk_bf16_f32 v84, v86, v87
	v_cvt_pk_bf16_f32 v85, v88, v89
	v_exp_f32_e32 v90, v90
	v_exp_f32_e32 v91, v91
	v_exp_f32_e32 v92, v92
	s_waitcnt lgkmcnt(4)
	v_mfma_f32_32x32x16_bf16 v[50:65], v[166:169], v[114:117], v[50:65]
	ds_read_b128 v[188:191], v217 offset:26656
	v_exp_f32_e32 v93, v93
	v_add_f32_e32 v171, v90, v171
	v_exp_f32_e32 v94, v94
	v_add_f32_e32 v197, v91, v197
	v_exp_f32_e32 v95, v95
	v_add_f32_e32 v171, v92, v171
	s_waitcnt lgkmcnt(4)
	v_mfma_f32_32x32x16_bf16 v[34:49], v[172:175], v[118:121], v[34:49]
	ds_read_b128 v[192:195], v217 offset:31264
	v_exp_f32_e32 v96, v96
	v_add_f32_e32 v197, v93, v197
	v_exp_f32_e32 v97, v97
	v_add_f32_e32 v171, v94, v171
	v_add_f32_e32 v197, v95, v197
	v_cvt_pk_bf16_f32 v90, v90, v91
	v_add_f32_e32 v171, v96, v171
	v_cvt_pk_bf16_f32 v91, v92, v93
	s_waitcnt lgkmcnt(4)
	v_mfma_f32_32x32x16_bf16 v[50:65], v[176:179], v[118:121], v[50:65]
	ds_read_b128 v[162:165], v217 offset:26688
	v_add_f32_e32 v197, v97, v197
	v_cvt_pk_bf16_f32 v92, v94, v95
	v_cvt_pk_bf16_f32 v93, v96, v97
	s_waitcnt lgkmcnt(4)
	v_mfma_f32_32x32x16_bf16 v[18:33], v[180:183], v[66:69], v[18:33]
	ds_read_b128 v[166:169], v217 offset:31296
	s_waitcnt lgkmcnt(4)
	v_mfma_f32_32x32x16_bf16 v[2:17], v[184:187], v[66:69], v[2:17]
	ds_read_b128 v[172:175], v217 offset:26720
	v_cmp_gt_i32_e64 vcc, 0, v241
	v_cmp_gt_i32_e64 s[42:43], 1, v241
	v_cmp_gt_i32_e64 s[44:45], 2, v241
	v_cmp_gt_i32_e64 s[46:47], 3, v241
	v_cmp_gt_i32_e64 s[48:49], 8, v241
	v_cmp_gt_i32_e64 s[50:51], 9, v241
	v_cndmask_b32_e64 v34, v34, v213, vcc
	v_cndmask_b32_e64 v35, v35, v213, s[42:43]
	v_cndmask_b32_e64 v36, v36, v213, s[44:45]
	v_cndmask_b32_e64 v37, v37, v213, s[46:47]
	v_cndmask_b32_e64 v38, v38, v213, s[48:49]
	v_cndmask_b32_e64 v39, v39, v213, s[50:51]
	v_cmp_gt_i32_e64 vcc, 10, v241
	v_cmp_gt_i32_e64 s[42:43], 11, v241
	v_cmp_gt_i32_e64 s[44:45], 16, v241
	v_cmp_gt_i32_e64 s[46:47], 17, v241
	v_cmp_gt_i32_e64 s[48:49], 18, v241
	v_cmp_gt_i32_e64 s[50:51], 19, v241
	v_cndmask_b32_e64 v40, v40, v213, vcc
	v_cndmask_b32_e64 v41, v41, v213, s[42:43]
	v_cndmask_b32_e64 v42, v42, v213, s[44:45]
	v_cndmask_b32_e64 v43, v43, v213, s[46:47]
	v_cndmask_b32_e64 v44, v44, v213, s[48:49]
	v_cndmask_b32_e64 v45, v45, v213, s[50:51]
	v_cmp_gt_i32_e64 vcc, 24, v241
	v_cmp_gt_i32_e64 s[42:43], 25, v241
	v_cmp_gt_i32_e64 s[44:45], 26, v241
	s_waitcnt lgkmcnt(4)
	v_mfma_f32_32x32x16_bf16 v[18:33], v[188:191], v[74:77], v[18:33]
	ds_read_b128 v[176:179], v217 offset:31328
	v_cmp_gt_i32_e64 s[46:47], 27, v241
	v_cmp_gt_i32_e64 s[48:49], 32, v241
	v_cmp_gt_i32_e64 s[50:51], 33, v241
	v_cndmask_b32_e64 v46, v46, v213, vcc
	v_cndmask_b32_e64 v47, v47, v213, s[42:43]
	v_cndmask_b32_e64 v48, v48, v213, s[44:45]
	v_cndmask_b32_e64 v49, v49, v213, s[46:47]
	v_cndmask_b32_e64 v50, v50, v213, s[48:49]
	v_cndmask_b32_e64 v51, v51, v213, s[50:51]
	s_waitcnt lgkmcnt(4)
	v_mfma_f32_32x32x16_bf16 v[2:17], v[192:195], v[74:77], v[2:17]
	s_waitcnt vmcnt(3)
	v_add_u32_e32 v196, 0x8800, v215
	ds_write_b128 v228, v[122:125]
	ds_write_b128 v238, v[126:129]
	ds_write2_b64 v196, v[138:139], v[140:141] offset0:128 offset1:130
	v_cmp_gt_i32_e64 vcc, 34, v241
	v_cmp_gt_i32_e64 s[42:43], 35, v241
	v_cmp_gt_i32_e64 s[44:45], 40, v241
	v_cmp_gt_i32_e64 s[46:47], 41, v241
	v_cmp_gt_i32_e64 s[48:49], 42, v241
	v_cmp_gt_i32_e64 s[50:51], 43, v241
	v_cndmask_b32_e64 v52, v52, v213, vcc
	v_cndmask_b32_e64 v53, v53, v213, s[42:43]
	v_cndmask_b32_e64 v54, v54, v213, s[44:45]
	v_cndmask_b32_e64 v55, v55, v213, s[46:47]
	s_waitcnt lgkmcnt(6)
	v_mfma_f32_32x32x16_bf16 v[18:33], v[162:165], v[82:85], v[18:33]
	v_cndmask_b32_e64 v56, v56, v213, s[48:49]
	v_cndmask_b32_e64 v57, v57, v213, s[50:51]
	v_cmp_gt_i32_e64 vcc, 48, v241
	v_cmp_gt_i32_e64 s[42:43], 49, v241
	v_cmp_gt_i32_e64 s[44:45], 50, v241
	v_cmp_gt_i32_e64 s[46:47], 51, v241
	v_cmp_gt_i32_e64 s[48:49], 56, v241
	v_cmp_gt_i32_e64 s[50:51], 57, v241
	v_cndmask_b32_e64 v58, v58, v213, vcc
	v_cndmask_b32_e64 v59, v59, v213, s[42:43]
	s_waitcnt lgkmcnt(5)
	v_mfma_f32_32x32x16_bf16 v[2:17], v[166:169], v[82:85], v[2:17]
	v_cndmask_b32_e64 v60, v60, v213, s[44:45]
	v_cndmask_b32_e64 v61, v61, v213, s[46:47]
	v_cndmask_b32_e64 v62, v62, v213, s[48:49]
	v_cndmask_b32_e64 v63, v63, v213, s[50:51]
	v_cmp_gt_i32_e64 vcc, 58, v241
	v_cmp_gt_i32_e64 s[42:43], 59, v241
	s_nop 1
	v_cndmask_b32_e64 v64, v64, v213, vcc
	v_cndmask_b32_e64 v65, v65, v213, s[42:43]
	v_max3_f32 v1, v34, v35, v36
	s_waitcnt lgkmcnt(4)
	v_mfma_f32_32x32x16_bf16 v[18:33], v[172:175], v[90:93], v[18:33]
	v_max3_f32 v170, v37, v38, v39
	v_max3_f32 v1, v1, v40, v41
	v_max3_f32 v170, v170, v42, v43
	v_max3_f32 v1, v1, v44, v45
	v_max3_f32 v170, v170, v46, v47
	v_max3_f32 v1, v1, v48, v49
	v_max3_f32 v170, v170, v50, v51
	v_max3_f32 v1, v1, v52, v53
	v_max3_f32 v170, v170, v54, v55
	v_max3_f32 v1, v1, v56, v57
	s_waitcnt lgkmcnt(3)
	v_mfma_f32_32x32x16_bf16 v[2:17], v[176:179], v[90:93], v[2:17]
	v_max3_f32 v170, v170, v58, v59
	v_max3_f32 v1, v1, v60, v61
	v_max3_f32 v170, v170, v62, v63
	v_max3_f32 v1, v1, v64, v65
	v_max_f32_e32 v1, v1, v170
	v_mov_b32_e32 v170, v1
	v_add_f32_e32 v171, v197, v171
	s_nop 0
	v_permlane32_swap_b32_e32 v1, v170
	v_max_f32_e32 v1, v1, v170
	v_cmp_lt_f32_e32 vcc, s93, v1
	s_cbranch_vccnz .Lmf_slow_m0

.Lmf_after_m0:
	s_add_i32 s84, s18, 1
	s_lshl_b32 s84, s84, 6
	s_cmp_gt_i32 s84, s19
	s_cbranch_scc1 .Lmf_idle_m1
	s_addk_i32 s84, 0x40
	s_cmp_gt_i32 s84, s19
	s_cbranch_scc1 .Lmf_conly_m1
	v_subrev_u32_e32 v241, s84, v240
	ds_read_b128 v[162:165], v216 offset:0
	ds_read_b128 v[166:169], v216 offset:6656
	ds_read_b128 v[172:175], v216 offset:32
	ds_read_b128 v[176:179], v216 offset:6688
	ds_read_b128 v[180:183], v216 offset:64
	global_load_dwordx4 v[122:125], v235, s[14:15]
	global_load_dwordx4 v[126:129], v236, s[14:15]
	s_add_u32 s14, s14, 0x18000
	s_addc_u32 s15, s15, 0
	global_load_dwordx4 v[138:141], v237, s[12:13]
	s_add_u32 s12, s12, 0x80
	s_addc_u32 s13, s13, 0
	s_waitcnt lgkmcnt(4)
	v_mfma_f32_32x32x16_bf16 v[66:81], v[162:165], v[98:101], v[146:161]
	ds_read_b128 v[184:187], v216 offset:6720
	v_exp_f32_e32 v34, v34
	v_exp_f32_e32 v35, v35
	v_exp_f32_e32 v36, v36
	v_exp_f32_e32 v37, v37
	v_add_f32_e32 v171, v34, v171
	v_exp_f32_e32 v38, v38
	s_waitcnt lgkmcnt(4)
	v_mfma_f32_32x32x16_bf16 v[82:97], v[166:169], v[98:101], v[146:161]
	ds_read_b128 v[188:191], v216 offset:96
	v_exp_f32_e32 v39, v39
	v_add_f32_e32 v171, v36, v171
	v_exp_f32_e32 v40, v40
	v_add_f32_e32 v197, v35, v37
	v_exp_f32_e32 v41, v41
	v_add_f32_e32 v171, v38, v171
	s_waitcnt lgkmcnt(4)
	v_mfma_f32_32x32x16_bf16 v[66:81], v[172:175], v[102:105], v[66:81]
	ds_read_b128 v[192:195], v216 offset:6752
	v_add_f32_e32 v197, v39, v197
	v_cvt_pk_bf16_f32 v34, v34, v35
	v_add_f32_e32 v171, v40, v171
	v_cvt_pk_bf16_f32 v35, v36, v37
	v_add_f32_e32 v197, v41, v197
	v_cvt_pk_bf16_f32 v36, v38, v39
	v_cvt_pk_bf16_f32 v37, v40, v41
	v_exp_f32_e32 v42, v42
	v_exp_f32_e32 v43, v43
	s_waitcnt lgkmcnt(4)
	v_mfma_f32_32x32x16_bf16 v[82:97], v[176:179], v[102:105], v[82:97]
	ds_read_b128 v[162:165], v216 offset:128
	v_exp_f32_e32 v44, v44
	v_exp_f32_e32 v45, v45
	v_add_f32_e32 v171, v42, v171
	v_exp_f32_e32 v46, v46
	v_add_f32_e32 v197, v43, v197
	v_exp_f32_e32 v47, v47
	s_waitcnt lgkmcnt(4)
	v_mfma_f32_32x32x16_bf16 v[66:81], v[180:183], v[106:109], v[66:81]
	ds_read_b128 v[166:169], v216 offset:6784
	v_add_f32_e32 v171, v44, v171
	v_exp_f32_e32 v48, v48
	v_add_f32_e32 v197, v45, v197
	v_exp_f32_e32 v49, v49
	v_add_f32_e32 v171, v46, v171
	v_add_f32_e32 v197, v47, v197
	s_waitcnt lgkmcnt(4)
	v_mfma_f32_32x32x16_bf16 v[82:97], v[184:187], v[106:109], v[82:97]
	ds_read_b128 v[172:175], v216 offset:160
	v_cvt_pk_bf16_f32 v42, v42, v43
	v_add_f32_e32 v171, v48, v171
	v_cvt_pk_bf16_f32 v43, v44, v45
	v_add_f32_e32 v197, v49, v197
	v_cvt_pk_bf16_f32 v44, v46, v47
	v_cvt_pk_bf16_f32 v45, v48, v49
	v_exp_f32_e32 v50, v50
	v_exp_f32_e32 v51, v51
	s_waitcnt lgkmcnt(4)
	v_mfma_f32_32x32x16_bf16 v[66:81], v[188:191], v[110:113], v[66:81]
	ds_read_b128 v[176:179], v216 offset:6816
	v_exp_f32_e32 v52, v52
	v_exp_f32_e32 v53, v53
	v_add_f32_e32 v171, v50, v171
	v_exp_f32_e32 v54, v54
	v_add_f32_e32 v197, v51, v197
	v_exp_f32_e32 v55, v55
	s_waitcnt lgkmcnt(4)
	v_mfma_f32_32x32x16_bf16 v[82:97], v[192:195], v[110:113], v[82:97]
	ds_read_b128 v[180:183], v217 offset:35840
	v_add_f32_e32 v171, v52, v171
	v_exp_f32_e32 v56, v56
	v_add_f32_e32 v197, v53, v197
	v_exp_f32_e32 v57, v57
	v_add_f32_e32 v171, v54, v171
	v_add_f32_e32 v197, v55, v197
	v_cvt_pk_bf16_f32 v50, v50, v51
	v_add_f32_e32 v171, v56, v171
	s_waitcnt lgkmcnt(4)
	v_mfma_f32_32x32x16_bf16 v[66:81], v[162:165], v[114:117], v[66:81]
	ds_read_b128 v[184:187], v217 offset:40448
	v_cvt_pk_bf16_f32 v51, v52, v53
	v_add_f32_e32 v197, v57, v197
	v_cvt_pk_bf16_f32 v52, v54, v55
	v_cvt_pk_bf16_f32 v53, v56, v57
	v_exp_f32_e32 v58, v58
	v_exp_f32_e32 v59, v59
	v_exp_f32_e32 v60, v60
	s_waitcnt lgkmcnt(4)
	v_mfma_f32_32x32x16_bf16 v[82:97], v[166:169], v[114:117], v[82:97]
	ds_read_b128 v[188:191], v217 offset:35872
	v_exp_f32_e32 v61, v61
	v_add_f32_e32 v171, v58, v171
	v_exp_f32_e32 v62, v62
	v_add_f32_e32 v197, v59, v197
	v_exp_f32_e32 v63, v63
	v_add_f32_e32 v171, v60, v171
	s_waitcnt lgkmcnt(4)
	v_mfma_f32_32x32x16_bf16 v[66:81], v[172:175], v[118:121], v[66:81]
	ds_read_b128 v[192:195], v217 offset:40480
	v_exp_f32_e32 v64, v64
	v_add_f32_e32 v197, v61, v197
	v_exp_f32_e32 v65, v65
	v_add_f32_e32 v171, v62, v171
	v_add_f32_e32 v197, v63, v197
	v_cvt_pk_bf16_f32 v58, v58, v59
	v_add_f32_e32 v171, v64, v171
	v_cvt_pk_bf16_f32 v59, v60, v61
	s_waitcnt lgkmcnt(4)
	v_mfma_f32_32x32x16_bf16 v[82:97], v[176:179], v[118:121], v[82:97]
	ds_read_b128 v[162:165], v217 offset:35904
	v_add_f32_e32 v197, v65, v197
	v_cvt_pk_bf16_f32 v60, v62, v63
	v_cvt_pk_bf16_f32 v61, v64, v65
	s_waitcnt lgkmcnt(4)
	v_mfma_f32_32x32x16_bf16 v[18:33], v[180:183], v[34:37], v[18:33]
	ds_read_b128 v[166:169], v217 offset:40512
	s_waitcnt lgkmcnt(4)
	v_mfma_f32_32x32x16_bf16 v[2:17], v[184:187], v[34:37], v[2:17]
	ds_read_b128 v[172:175], v217 offset:35936
	v_cmp_gt_i32_e64 vcc, 0, v241
	v_cmp_gt_i32_e64 s[42:43], 1, v241
	v_cmp_gt_i32_e64 s[44:45], 2, v241
	v_cmp_gt_i32_e64 s[46:47], 3, v241
	v_cmp_gt_i32_e64 s[48:49], 8, v241
	v_cmp_gt_i32_e64 s[50:51], 9, v241
	v_cndmask_b32_e64 v66, v66, v213, vcc
	v_cndmask_b32_e64 v67, v67, v213, s[42:43]
	v_cndmask_b32_e64 v68, v68, v213, s[44:45]
	v_cndmask_b32_e64 v69, v69, v213, s[46:47]
	v_cndmask_b32_e64 v70, v70, v213, s[48:49]
	v_cndmask_b32_e64 v71, v71, v213, s[50:51]
	v_cmp_gt_i32_e64 vcc, 10, v241
	v_cmp_gt_i32_e64 s[42:43], 11, v241
	v_cmp_gt_i32_e64 s[44:45], 16, v241
	v_cmp_gt_i32_e64 s[46:47], 17, v241
	v_cmp_gt_i32_e64 s[48:49], 18, v241
	v_cmp_gt_i32_e64 s[50:51], 19, v241
	v_cndmask_b32_e64 v72, v72, v213, vcc
	v_cndmask_b32_e64 v73, v73, v213, s[42:43]
	v_cndmask_b32_e64 v74, v74, v213, s[44:45]
	v_cndmask_b32_e64 v75, v75, v213, s[46:47]
	v_cndmask_b32_e64 v76, v76, v213, s[48:49]
	v_cndmask_b32_e64 v77, v77, v213, s[50:51]
	v_cmp_gt_i32_e64 vcc, 24, v241
	v_cmp_gt_i32_e64 s[42:43], 25, v241
	v_cmp_gt_i32_e64 s[44:45], 26, v241
	s_waitcnt lgkmcnt(4)
	v_mfma_f32_32x32x16_bf16 v[18:33], v[188:191], v[42:45], v[18:33]
	ds_read_b128 v[176:179], v217 offset:40544
	v_cmp_gt_i32_e64 s[46:47], 27, v241
	v_cmp_gt_i32_e64 s[48:49], 32, v241
	v_cmp_gt_i32_e64 s[50:51], 33, v241
	v_cndmask_b32_e64 v78, v78, v213, vcc
	v_cndmask_b32_e64 v79, v79, v213, s[42:43]
	v_cndmask_b32_e64 v80, v80, v213, s[44:45]
	v_cndmask_b32_e64 v81, v81, v213, s[46:47]
	v_cndmask_b32_e64 v82, v82, v213, s[48:49]
	v_cndmask_b32_e64 v83, v83, v213, s[50:51]
	s_waitcnt lgkmcnt(4)
	v_mfma_f32_32x32x16_bf16 v[2:17], v[192:195], v[42:45], v[2:17]
	s_waitcnt vmcnt(3)
	ds_write_b128 v228, v[130:133] offset:13312
	ds_write_b128 v238, v[134:137] offset:13312
	ds_write2_b64 v225, v[142:143], v[144:145] offset1:2
	v_cmp_gt_i32_e64 vcc, 34, v241
	v_cmp_gt_i32_e64 s[42:43], 35, v241
	v_cmp_gt_i32_e64 s[44:45], 40, v241
	v_cmp_gt_i32_e64 s[46:47], 41, v241
	v_cmp_gt_i32_e64 s[48:49], 42, v241
	v_cmp_gt_i32_e64 s[50:51], 43, v241
	v_cndmask_b32_e64 v84, v84, v213, vcc
	v_cndmask_b32_e64 v85, v85, v213, s[42:43]
	v_cndmask_b32_e64 v86, v86, v213, s[44:45]
	v_cndmask_b32_e64 v87, v87, v213, s[46:47]
	s_waitcnt lgkmcnt(6)
	v_mfma_f32_32x32x16_bf16 v[18:33], v[162:165], v[50:53], v[18:33]
	v_cndmask_b32_e64 v88, v88, v213, s[48:49]
	v_cndmask_b32_e64 v89, v89, v213, s[50:51]
	v_cmp_gt_i32_e64 vcc, 48, v241
	v_cmp_gt_i32_e64 s[42:43], 49, v241
	v_cmp_gt_i32_e64 s[44:45], 50, v241
	v_cmp_gt_i32_e64 s[46:47], 51, v241
	v_cmp_gt_i32_e64 s[48:49], 56, v241
	v_cmp_gt_i32_e64 s[50:51], 57, v241
	v_cndmask_b32_e64 v90, v90, v213, vcc
	v_cndmask_b32_e64 v91, v91, v213, s[42:43]
	s_waitcnt lgkmcnt(5)
	v_mfma_f32_32x32x16_bf16 v[2:17], v[166:169], v[50:53], v[2:17]
	v_cndmask_b32_e64 v92, v92, v213, s[44:45]
	v_cndmask_b32_e64 v93, v93, v213, s[46:47]
	v_cndmask_b32_e64 v94, v94, v213, s[48:49]
	v_cndmask_b32_e64 v95, v95, v213, s[50:51]
	v_cmp_gt_i32_e64 vcc, 58, v241
	v_cmp_gt_i32_e64 s[42:43], 59, v241
	s_nop 1
	v_cndmask_b32_e64 v96, v96, v213, vcc
	v_cndmask_b32_e64 v97, v97, v213, s[42:43]
	v_max3_f32 v1, v66, v67, v68
	s_waitcnt lgkmcnt(4)
	v_mfma_f32_32x32x16_bf16 v[18:33], v[172:175], v[58:61], v[18:33]
	v_max3_f32 v170, v69, v70, v71
	v_max3_f32 v1, v1, v72, v73
	v_max3_f32 v170, v170, v74, v75
	v_max3_f32 v1, v1, v76, v77
	v_max3_f32 v170, v170, v78, v79
	v_max3_f32 v1, v1, v80, v81
	v_max3_f32 v170, v170, v82, v83
	v_max3_f32 v1, v1, v84, v85
	v_max3_f32 v170, v170, v86, v87
	v_max3_f32 v1, v1, v88, v89
	s_waitcnt lgkmcnt(3)
	v_mfma_f32_32x32x16_bf16 v[2:17], v[176:179], v[58:61], v[2:17]
	v_max3_f32 v170, v170, v90, v91
	v_max3_f32 v1, v1, v92, v93
	v_max3_f32 v170, v170, v94, v95
	v_max3_f32 v1, v1, v96, v97
	v_max_f32_e32 v1, v1, v170
	v_mov_b32_e32 v170, v1
	v_add_f32_e32 v171, v197, v171
	s_nop 0
	v_permlane32_swap_b32_e32 v1, v170
	v_max_f32_e32 v1, v1, v170
	v_cmp_lt_f32_e32 vcc, s93, v1
	s_cbranch_vccnz .Lmf_slow_m1

.Lmf_after_m1:
	s_add_i32 s18, s18, 2
	s_add_i32 s17, s17, -1
	s_cmp_lg_u32 s17, 0
	s_cbranch_scc1 .Lmf_mloop
	s_mov_b32 s83, s18
	s_branch .Lmf_exit

.Lmf_idle_m0:
	global_load_dwordx4 v[130:133], v235, s[14:15]
	global_load_dwordx4 v[134:137], v236, s[14:15]
	s_add_u32 s14, s14, 0x18000
	s_addc_u32 s15, s15, 0
	global_load_dwordx4 v[142:145], v237, s[12:13]
	s_add_u32 s12, s12, 0x80
	s_addc_u32 s13, s13, 0
	s_waitcnt vmcnt(3)
	v_add_u32_e32 v196, 0x8800, v215
	ds_write_b128 v228, v[122:125]
	ds_write_b128 v238, v[126:129]
	ds_write2_b64 v196, v[138:139], v[140:141] offset0:128 offset1:130
	s_waitcnt lgkmcnt(0)
	s_barrier
	s_branch .Lmf_after_m0
.Lmf_conly_m0:
	ds_read_b128 v[162:165], v217 offset:26624
	ds_read_b128 v[166:169], v217 offset:31232
	ds_read_b128 v[172:175], v217 offset:26656
	ds_read_b128 v[176:179], v217 offset:31264
	ds_read_b128 v[180:183], v217 offset:26688
	global_load_dwordx4 v[130:133], v235, s[14:15]
	global_load_dwordx4 v[134:137], v236, s[14:15]
	s_add_u32 s14, s14, 0x18000
	s_addc_u32 s15, s15, 0
	global_load_dwordx4 v[142:145], v237, s[12:13]
	s_add_u32 s12, s12, 0x80
	s_addc_u32 s13, s13, 0
	v_exp_f32_e32 v66, v66
	v_exp_f32_e32 v67, v67
	v_exp_f32_e32 v68, v68
	v_exp_f32_e32 v69, v69
	v_add_f32_e32 v171, v66, v171
	v_exp_f32_e32 v70, v70
	v_exp_f32_e32 v71, v71
	v_add_f32_e32 v171, v68, v171
	v_exp_f32_e32 v72, v72
	v_add_f32_e32 v197, v67, v69
	v_exp_f32_e32 v73, v73
	v_add_f32_e32 v171, v70, v171
	v_add_f32_e32 v197, v71, v197
	v_cvt_pk_bf16_f32 v66, v66, v67
	v_add_f32_e32 v171, v72, v171
	v_cvt_pk_bf16_f32 v67, v68, v69
	v_add_f32_e32 v197, v73, v197
	v_cvt_pk_bf16_f32 v68, v70, v71
	v_cvt_pk_bf16_f32 v69, v72, v73
	v_exp_f32_e32 v74, v74
	s_waitcnt lgkmcnt(4)
	v_mfma_f32_32x32x16_bf16 v[18:33], v[162:165], v[66:69], v[18:33]
	ds_read_b128 v[184:187], v217 offset:31296
	v_exp_f32_e32 v75, v75
	v_exp_f32_e32 v76, v76
	v_exp_f32_e32 v77, v77
	v_add_f32_e32 v171, v74, v171
	v_exp_f32_e32 v78, v78
	v_add_f32_e32 v197, v75, v197
	s_waitcnt lgkmcnt(4)
	v_mfma_f32_32x32x16_bf16 v[2:17], v[166:169], v[66:69], v[2:17]
	ds_read_b128 v[188:191], v217 offset:26720
	v_exp_f32_e32 v79, v79
	v_add_f32_e32 v171, v76, v171
	v_exp_f32_e32 v80, v80
	v_add_f32_e32 v197, v77, v197
	v_exp_f32_e32 v81, v81
	v_add_f32_e32 v171, v78, v171
	v_add_f32_e32 v197, v79, v197
	v_cvt_pk_bf16_f32 v74, v74, v75
	v_add_f32_e32 v171, v80, v171
	v_cvt_pk_bf16_f32 v75, v76, v77
	v_add_f32_e32 v197, v81, v197
	v_cvt_pk_bf16_f32 v76, v78, v79
	v_cvt_pk_bf16_f32 v77, v80, v81
	s_nop 0
	s_waitcnt lgkmcnt(4)
	v_mfma_f32_32x32x16_bf16 v[18:33], v[172:175], v[74:77], v[18:33]
	ds_read_b128 v[192:195], v217 offset:31328
	v_exp_f32_e32 v82, v82
	v_exp_f32_e32 v83, v83
	v_exp_f32_e32 v84, v84
	s_waitcnt lgkmcnt(4)
	v_mfma_f32_32x32x16_bf16 v[2:17], v[176:179], v[74:77], v[2:17]
	s_waitcnt vmcnt(3)
	v_add_u32_e32 v196, 0x8800, v215
	ds_write_b128 v228, v[122:125]
	ds_write_b128 v238, v[126:129]
	ds_write2_b64 v196, v[138:139], v[140:141] offset0:128 offset1:130
	v_exp_f32_e32 v85, v85
	v_add_f32_e32 v171, v82, v171
	v_exp_f32_e32 v86, v86
	v_add_f32_e32 v197, v83, v197
	v_exp_f32_e32 v87, v87
	v_add_f32_e32 v171, v84, v171
	v_exp_f32_e32 v88, v88
	v_add_f32_e32 v197, v85, v197
	v_exp_f32_e32 v89, v89
	v_add_f32_e32 v171, v86, v171
	v_add_f32_e32 v197, v87, v197
	v_cvt_pk_bf16_f32 v82, v82, v83
	v_add_f32_e32 v171, v88, v171
	v_cvt_pk_bf16_f32 v83, v84, v85
	v_add_f32_e32 v197, v89, v197
	v_cvt_pk_bf16_f32 v84, v86, v87
	v_cvt_pk_bf16_f32 v85, v88, v89
	s_nop 0
	s_waitcnt lgkmcnt(6)
	v_mfma_f32_32x32x16_bf16 v[18:33], v[180:183], v[82:85], v[18:33]
	s_waitcnt lgkmcnt(5)
	v_mfma_f32_32x32x16_bf16 v[2:17], v[184:187], v[82:85], v[2:17]
	v_exp_f32_e32 v90, v90
	v_exp_f32_e32 v91, v91
	v_exp_f32_e32 v92, v92
	v_exp_f32_e32 v93, v93
	v_add_f32_e32 v171, v90, v171
	v_exp_f32_e32 v94, v94
	v_add_f32_e32 v197, v91, v197
	v_exp_f32_e32 v95, v95
	v_add_f32_e32 v171, v92, v171
	v_exp_f32_e32 v96, v96
	v_add_f32_e32 v197, v93, v197
	v_exp_f32_e32 v97, v97
	v_add_f32_e32 v171, v94, v171
	v_add_f32_e32 v197, v95, v197
	v_cvt_pk_bf16_f32 v90, v90, v91
	v_add_f32_e32 v171, v96, v171
	v_cvt_pk_bf16_f32 v91, v92, v93
	v_add_f32_e32 v197, v97, v197
	v_cvt_pk_bf16_f32 v92, v94, v95
	v_cvt_pk_bf16_f32 v93, v96, v97
	s_nop 0
	s_waitcnt lgkmcnt(4)
	v_mfma_f32_32x32x16_bf16 v[18:33], v[188:191], v[90:93], v[18:33]
	s_waitcnt lgkmcnt(3)
	v_mfma_f32_32x32x16_bf16 v[2:17], v[192:195], v[90:93], v[2:17]
	v_add_f32_e32 v171, v197, v171
	s_waitcnt lgkmcnt(0)
	s_barrier
	s_branch .Lmf_after_m0
.Lmf_idle_m1:
	global_load_dwordx4 v[122:125], v235, s[14:15]
	global_load_dwordx4 v[126:129], v236, s[14:15]
	s_add_u32 s14, s14, 0x18000
	s_addc_u32 s15, s15, 0
	global_load_dwordx4 v[138:141], v237, s[12:13]
	s_add_u32 s12, s12, 0x80
	s_addc_u32 s13, s13, 0
	s_waitcnt vmcnt(3)
	ds_write_b128 v228, v[130:133] offset:13312
	ds_write_b128 v238, v[134:137] offset:13312
	ds_write2_b64 v225, v[142:143], v[144:145] offset1:2
	s_waitcnt lgkmcnt(0)
	s_barrier
	s_branch .Lmf_after_m1
.Lmf_conly_m1:
	ds_read_b128 v[162:165], v217 offset:35840
	ds_read_b128 v[166:169], v217 offset:40448
	ds_read_b128 v[172:175], v217 offset:35872
	ds_read_b128 v[176:179], v217 offset:40480
	ds_read_b128 v[180:183], v217 offset:35904
	global_load_dwordx4 v[122:125], v235, s[14:15]
	global_load_dwordx4 v[126:129], v236, s[14:15]
	s_add_u32 s14, s14, 0x18000
	s_addc_u32 s15, s15, 0
	global_load_dwordx4 v[138:141], v237, s[12:13]
	s_add_u32 s12, s12, 0x80
	s_addc_u32 s13, s13, 0
	v_exp_f32_e32 v34, v34
	v_exp_f32_e32 v35, v35
	v_exp_f32_e32 v36, v36
	v_exp_f32_e32 v37, v37
	v_add_f32_e32 v171, v34, v171
	v_exp_f32_e32 v38, v38
	v_exp_f32_e32 v39, v39
	v_add_f32_e32 v171, v36, v171
	v_exp_f32_e32 v40, v40
	v_add_f32_e32 v197, v35, v37
	v_exp_f32_e32 v41, v41
	v_add_f32_e32 v171, v38, v171
	v_add_f32_e32 v197, v39, v197
	v_cvt_pk_bf16_f32 v34, v34, v35
	v_add_f32_e32 v171, v40, v171
	v_cvt_pk_bf16_f32 v35, v36, v37
	v_add_f32_e32 v197, v41, v197
	v_cvt_pk_bf16_f32 v36, v38, v39
	v_cvt_pk_bf16_f32 v37, v40, v41
	v_exp_f32_e32 v42, v42
	s_waitcnt lgkmcnt(4)
	v_mfma_f32_32x32x16_bf16 v[18:33], v[162:165], v[34:37], v[18:33]
	ds_read_b128 v[184:187], v217 offset:40512
	v_exp_f32_e32 v43, v43
	v_exp_f32_e32 v44, v44
	v_exp_f32_e32 v45, v45
	v_add_f32_e32 v171, v42, v171
	v_exp_f32_e32 v46, v46
	v_add_f32_e32 v197, v43, v197
	s_waitcnt lgkmcnt(4)
	v_mfma_f32_32x32x16_bf16 v[2:17], v[166:169], v[34:37], v[2:17]
	ds_read_b128 v[188:191], v217 offset:35936
	v_exp_f32_e32 v47, v47
	v_add_f32_e32 v171, v44, v171
	v_exp_f32_e32 v48, v48
	v_add_f32_e32 v197, v45, v197
	v_exp_f32_e32 v49, v49
	v_add_f32_e32 v171, v46, v171
	v_add_f32_e32 v197, v47, v197
	v_cvt_pk_bf16_f32 v42, v42, v43
	v_add_f32_e32 v171, v48, v171
	v_cvt_pk_bf16_f32 v43, v44, v45
	v_add_f32_e32 v197, v49, v197
	v_cvt_pk_bf16_f32 v44, v46, v47
	v_cvt_pk_bf16_f32 v45, v48, v49
	s_nop 0
	s_waitcnt lgkmcnt(4)
	v_mfma_f32_32x32x16_bf16 v[18:33], v[172:175], v[42:45], v[18:33]
	ds_read_b128 v[192:195], v217 offset:40544
	v_exp_f32_e32 v50, v50
	v_exp_f32_e32 v51, v51
	v_exp_f32_e32 v52, v52
	s_waitcnt lgkmcnt(4)
	v_mfma_f32_32x32x16_bf16 v[2:17], v[176:179], v[42:45], v[2:17]
	s_waitcnt vmcnt(3)
	ds_write_b128 v228, v[130:133] offset:13312
	ds_write_b128 v238, v[134:137] offset:13312
	ds_write2_b64 v225, v[142:143], v[144:145] offset1:2
	v_exp_f32_e32 v53, v53
	v_add_f32_e32 v171, v50, v171
	v_exp_f32_e32 v54, v54
	v_add_f32_e32 v197, v51, v197
	v_exp_f32_e32 v55, v55
	v_add_f32_e32 v171, v52, v171
	v_exp_f32_e32 v56, v56
	v_add_f32_e32 v197, v53, v197
	v_exp_f32_e32 v57, v57
	v_add_f32_e32 v171, v54, v171
	v_add_f32_e32 v197, v55, v197
	v_cvt_pk_bf16_f32 v50, v50, v51
	v_add_f32_e32 v171, v56, v171
	v_cvt_pk_bf16_f32 v51, v52, v53
	v_add_f32_e32 v197, v57, v197
	v_cvt_pk_bf16_f32 v52, v54, v55
	v_cvt_pk_bf16_f32 v53, v56, v57
	s_nop 0
	s_waitcnt lgkmcnt(6)
	v_mfma_f32_32x32x16_bf16 v[18:33], v[180:183], v[50:53], v[18:33]
	s_waitcnt lgkmcnt(5)
	v_mfma_f32_32x32x16_bf16 v[2:17], v[184:187], v[50:53], v[2:17]
	v_exp_f32_e32 v58, v58
	v_exp_f32_e32 v59, v59
	v_exp_f32_e32 v60, v60
	v_exp_f32_e32 v61, v61
	v_add_f32_e32 v171, v58, v171
	v_exp_f32_e32 v62, v62
	v_add_f32_e32 v197, v59, v197
	v_exp_f32_e32 v63, v63
	v_add_f32_e32 v171, v60, v171
	v_exp_f32_e32 v64, v64
	v_add_f32_e32 v197, v61, v197
	v_exp_f32_e32 v65, v65
	v_add_f32_e32 v171, v62, v171
	v_add_f32_e32 v197, v63, v197
	v_cvt_pk_bf16_f32 v58, v58, v59
	v_add_f32_e32 v171, v64, v171
	v_cvt_pk_bf16_f32 v59, v60, v61
	v_add_f32_e32 v197, v65, v197
	v_cvt_pk_bf16_f32 v60, v62, v63
	v_cvt_pk_bf16_f32 v61, v64, v65
	s_nop 0
	s_waitcnt lgkmcnt(4)
	v_mfma_f32_32x32x16_bf16 v[18:33], v[188:191], v[58:61], v[18:33]
	s_waitcnt lgkmcnt(3)
	v_mfma_f32_32x32x16_bf16 v[2:17], v[192:195], v[58:61], v[2:17]
	v_add_f32_e32 v171, v197, v171
	s_waitcnt lgkmcnt(0)
	s_barrier
	s_branch .Lmf_after_m1
